# v80 + P3 counted waits at the consumer sites: batch-2 copy site vmcnt(45) (lambda/row loads may stay in flight), assemble copies behind their own vmcnt(34)
# speedup vs baseline: 1.0245x; 1.0245x over previous
.LBB0_956:
	s_or_b64 exec, exec, s[4:5]
	v_ashrrev_i32_e32 v1, 4, v84
	v_lshl_add_u32 v232, s6, 5, v1
	v_lshlrev_b32_e32 v233, 4, v84
	s_ashr_i32 s1, s0, 31
	v_and_b32_e32 v85, 0xf0, v233
	s_lshl_b64 s[4:5], s[0:1], 12
	v_ashrrev_i32_e32 v233, 31, v232
	v_lshl_add_u64 v[234:235], s[4:5], 0, v[232:233]
	v_lshlrev_b64 v[234:235], 9, v[234:235]
	v_ashrrev_i32_e32 v232, 1, v232
	s_lshl_b64 s[8:9], s[0:1], 21
	v_bfi_b32 v232, -16, v232, v84
	v_lshl_add_u64 v[234:235], s[96:97], 0, v[234:235]
	v_lshlrev_b32_e32 v82, 1, v85
	v_mov_b32_e32 v83, 0
	s_add_u32 s8, s96, s8
	v_ashrrev_i32_e32 v233, 31, v232
	v_lshl_add_u64 v[88:89], v[234:235], 0, v[82:83]
	s_mov_b32 s7, 0x23b80000
	s_addc_u32 s9, s97, s9
	v_lshlrev_b64 v[232:233], 10, v[232:233]
	v_add_co_u32_e32 v234, vcc, s7, v88
	v_lshl_add_u64 v[232:233], s[8:9], 0, v[232:233]
	s_nop 0
	v_addc_co_u32_e32 v235, vcc, 0, v89, vcc
	s_mov_b64 s[8:9], 0x23b80000
	v_lshl_add_u64 v[234:235], v[88:89], 0, s[8:9]
	s_mov_b32 s7, 0x23ba0000
	v_add_co_u32_e32 v234, vcc, s7, v88
	v_and_b32_e32 v82, 0x1f0, v84
	s_mov_b64 s[8:9], 0x23ba0000
	v_addc_co_u32_e32 v235, vcc, 0, v89, vcc
	v_lshl_add_u64 v[86:87], v[232:233], 0, v[82:83]
	v_lshl_add_u64 v[232:233], v[88:89], 0, s[8:9]
	s_mov_b32 s7, 0x23bc0000
	v_add_co_u32_e32 v234, vcc, s7, v88
	s_mov_b64 s[8:9], 0x23bc0000
	s_nop 0
	v_addc_co_u32_e32 v235, vcc, 0, v89, vcc
	v_lshl_add_u64 v[232:233], v[88:89], 0, s[8:9]
	s_mov_b32 s7, 0x23be0000
	v_add_co_u32_e32 v234, vcc, s7, v88
	s_mov_b64 s[8:9], 0x23be0000
	s_nop 0
	v_addc_co_u32_e32 v235, vcc, 0, v89, vcc
	v_lshl_add_u64 v[232:233], v[88:89], 0, s[8:9]
	s_mov_b32 s7, 0x23c00000
	v_add_co_u32_e32 v234, vcc, s7, v88
	s_mov_b64 s[8:9], 0x23c00000
	s_nop 0
	v_addc_co_u32_e32 v235, vcc, 0, v89, vcc
	v_lshl_add_u64 v[232:233], v[88:89], 0, s[8:9]
	s_mov_b32 s7, 0x23c20000
	v_add_co_u32_e32 v234, vcc, s7, v88
	s_mov_b64 s[8:9], 0x23c20000
	s_nop 0
	v_addc_co_u32_e32 v235, vcc, 0, v89, vcc
	v_lshl_add_u64 v[232:233], v[88:89], 0, s[8:9]
	s_mov_b32 s7, 0x23c40000
	v_add_co_u32_e32 v234, vcc, s7, v88
	s_mov_b64 s[8:9], 0x23c40000
	s_nop 0
	v_addc_co_u32_e32 v235, vcc, 0, v89, vcc
	v_lshl_add_u64 v[232:233], v[88:89], 0, s[8:9]
	s_mov_b32 s7, 0x23c60000
	v_add_co_u32_e32 v240, vcc, s7, v88
	s_mov_b64 s[8:9], 0x23c60000
	s_nop 0
	v_addc_co_u32_e32 v241, vcc, 0, v89, vcc
	v_lshl_add_u64 v[242:243], v[88:89], 0, s[8:9]
	ds_read_b128 v[54:57], v83
	ds_read_b128 v[58:61], v83 offset:64
	ds_read_b128 v[66:69], v83 offset:16
	s_mov_b32 s7, 0x27ba0000
	v_add_co_u32_e32 v102, vcc, s7, v86
	s_waitcnt lgkmcnt(2)
	v_mul_f32_e32 v82, 0, v54
	v_addc_co_u32_e32 v103, vcc, 0, v87, vcc
	s_mov_b32 s7, 0x27bc0000
	ds_read_b128 v[70:73], v83 offset:80
	s_mov_b64 s[8:9], 0x23c80000
	v_lshlrev_b32_e32 v1, 2, v1
	v_readlane_b32 s36, v245, 25
	v_readlane_b32 s50, v245, 39
	v_readlane_b32 s51, v245, 40
	s_movk_i32 s10, 0x84
	v_readlane_b32 s37, v245, 26
	v_readlane_b32 s38, v245, 27
	v_readlane_b32 s39, v245, 28
	s_waitcnt vmcnt(60)
	v_lshlrev_b32_e32 v90, 16, v78
	v_and_b32_e32 v91, 0xffff0000, v78
	s_waitcnt vmcnt(59)
	v_lshlrev_b32_e32 v94, 16, v74
	v_and_b32_e32 v95, 0xffff0000, v74
	v_lshlrev_b32_e32 v74, 16, v75
	v_and_b32_e32 v75, 0xffff0000, v75
	v_lshlrev_b32_e32 v78, 16, v79
	v_and_b32_e32 v79, 0xffff0000, v79
	v_lshlrev_b32_e32 v92, 16, v80
	v_and_b32_e32 v93, 0xffff0000, v80
	v_lshlrev_b32_e32 v80, 16, v81
	v_and_b32_e32 v81, 0xffff0000, v81
	s_waitcnt lgkmcnt(2)
	v_pk_fma_f32 v[96:97], v[58:59], v[74:75], v[82:83] op_sel_hi:[0,1,0]
	v_lshlrev_b32_e32 v74, 16, v76
	v_and_b32_e32 v75, 0xffff0000, v76
	v_pk_fma_f32 v[90:91], v[58:59], v[90:91], v[82:83] op_sel_hi:[0,1,0]
	v_pk_fma_f32 v[78:79], v[58:59], v[78:79], v[82:83] op_sel_hi:[0,1,0]
	v_pk_fma_f32 v[92:93], v[58:59], v[92:93], v[82:83] op_sel_hi:[0,1,0]
	v_pk_fma_f32 v[80:81], v[58:59], v[80:81], v[82:83] op_sel_hi:[0,1,0]
	v_pk_fma_f32 v[98:99], v[58:59], v[74:75], v[82:83] op_sel_hi:[0,1,0]
	v_lshlrev_b32_e32 v74, 16, v77
	v_and_b32_e32 v75, 0xffff0000, v77
	v_pk_fma_f32 v[94:95], v[58:59], v[94:95], v[82:83] op_sel_hi:[0,1,0]
	v_pk_fma_f32 v[100:101], v[58:59], v[74:75], v[82:83] op_sel_hi:[0,1,0]
	v_cvt_pk_bf16_f32 v74, v90, v91
	v_cvt_pk_bf16_f32 v75, v78, v79
	v_cvt_pk_bf16_f32 v76, v92, v93
	v_cvt_pk_bf16_f32 v77, v80, v81
	global_store_dwordx4 v[102:103], v[74:77], off
	v_readlane_b32 s40, v245, 29
	v_readlane_b32 s41, v245, 30
	v_cvt_pk_bf16_f32 v74, v94, v95
	v_cvt_pk_bf16_f32 v75, v96, v97
	v_cvt_pk_bf16_f32 v76, v98, v99
	v_cvt_pk_bf16_f32 v77, v100, v101
	global_store_dwordx4 v[102:103], v[74:77], off offset:512
	v_readlane_b32 s42, v245, 31
	v_readlane_b32 s43, v245, 32
	s_waitcnt vmcnt(60)
	v_lshlrev_b32_e32 v74, 16, v62
	v_and_b32_e32 v75, 0xffff0000, v62
	v_lshlrev_b32_e32 v62, 16, v63
	v_and_b32_e32 v63, 0xffff0000, v63
	v_pk_mul_f32 v[62:63], v[58:59], v[62:63] op_sel:[1,0]
	v_lshlrev_b32_e32 v76, 16, v64
	v_pk_fma_f32 v[62:63], v[78:79], v[54:55], v[62:63] op_sel:[0,1,0]
	v_and_b32_e32 v77, 0xffff0000, v64
	v_lshlrev_b32_e32 v64, 16, v65
	v_and_b32_e32 v65, 0xffff0000, v65
	s_waitcnt vmcnt(59)
	v_lshlrev_b32_e32 v78, 16, v50
	v_and_b32_e32 v79, 0xffff0000, v50
	v_lshlrev_b32_e32 v50, 16, v51
	v_and_b32_e32 v51, 0xffff0000, v51
	v_pk_mul_f32 v[64:65], v[58:59], v[64:65] op_sel:[1,0]
	v_pk_mul_f32 v[50:51], v[58:59], v[50:51] op_sel:[1,0]
	v_pk_fma_f32 v[64:65], v[80:81], v[54:55], v[64:65] op_sel:[0,1,0]
	v_pk_fma_f32 v[80:81], v[96:97], v[54:55], v[50:51] op_sel:[0,1,0]
	v_lshlrev_b32_e32 v50, 16, v52
	v_and_b32_e32 v51, 0xffff0000, v52
	v_pk_mul_f32 v[74:75], v[58:59], v[74:75] op_sel:[1,0]
	v_pk_mul_f32 v[50:51], v[58:59], v[50:51] op_sel:[1,0]
	v_pk_fma_f32 v[74:75], v[90:91], v[54:55], v[74:75] op_sel:[0,1,0]
	v_pk_mul_f32 v[76:77], v[58:59], v[76:77] op_sel:[1,0]
	v_pk_fma_f32 v[90:91], v[98:99], v[54:55], v[50:51] op_sel:[0,1,0]
	v_lshlrev_b32_e32 v50, 16, v53
	v_and_b32_e32 v51, 0xffff0000, v53
	v_pk_fma_f32 v[76:77], v[92:93], v[54:55], v[76:77] op_sel:[0,1,0]
	v_pk_mul_f32 v[78:79], v[58:59], v[78:79] op_sel:[1,0]
	v_pk_mul_f32 v[50:51], v[58:59], v[50:51] op_sel:[1,0]
	v_add_co_u32_e32 v58, vcc, s7, v86
	v_pk_fma_f32 v[78:79], v[94:95], v[54:55], v[78:79] op_sel:[0,1,0]
	v_pk_fma_f32 v[54:55], v[100:101], v[54:55], v[50:51] op_sel:[0,1,0]
	v_cvt_pk_bf16_f32 v50, v74, v75
	v_cvt_pk_bf16_f32 v51, v62, v63
	v_cvt_pk_bf16_f32 v52, v76, v77
	v_cvt_pk_bf16_f32 v53, v64, v65
	v_addc_co_u32_e32 v59, vcc, 0, v87, vcc
	global_store_dwordx4 v[58:59], v[50:53], off
	s_mov_b32 s7, 0x27be0000
	v_readlane_b32 s44, v245, 33
	v_cvt_pk_bf16_f32 v50, v78, v79
	v_cvt_pk_bf16_f32 v51, v80, v81
	v_cvt_pk_bf16_f32 v52, v90, v91
	v_cvt_pk_bf16_f32 v53, v54, v55
	global_store_dwordx4 v[58:59], v[50:53], off offset:512
	s_waitcnt vmcnt(59)
	v_lshlrev_b32_e32 v58, 16, v42
	v_and_b32_e32 v59, 0xffff0000, v42
	v_lshlrev_b32_e32 v50, 16, v46
	v_and_b32_e32 v51, 0xffff0000, v46
	v_lshlrev_b32_e32 v46, 16, v47
	v_and_b32_e32 v47, 0xffff0000, v47
	v_lshlrev_b32_e32 v42, 16, v43
	v_and_b32_e32 v43, 0xffff0000, v43
	v_pk_mul_f32 v[46:47], v[60:61], v[46:47] op_sel_hi:[0,1]
	v_pk_mul_f32 v[42:43], v[60:61], v[42:43] op_sel_hi:[0,1]
	v_pk_fma_f32 v[46:47], v[62:63], v[56:57], v[46:47] op_sel_hi:[1,0,1]
	v_lshlrev_b32_e32 v52, 16, v48
	v_and_b32_e32 v53, 0xffff0000, v48
	v_lshlrev_b32_e32 v48, 16, v49
	v_and_b32_e32 v49, 0xffff0000, v49
	v_pk_fma_f32 v[62:63], v[80:81], v[56:57], v[42:43] op_sel_hi:[1,0,1]
	v_lshlrev_b32_e32 v42, 16, v44
	v_and_b32_e32 v43, 0xffff0000, v44
	v_pk_mul_f32 v[48:49], v[60:61], v[48:49] op_sel_hi:[0,1]
	v_pk_mul_f32 v[42:43], v[60:61], v[42:43] op_sel_hi:[0,1]
	v_pk_mul_f32 v[50:51], v[60:61], v[50:51] op_sel_hi:[0,1]
	v_pk_mul_f32 v[52:53], v[60:61], v[52:53] op_sel_hi:[0,1]
	v_pk_fma_f32 v[48:49], v[64:65], v[56:57], v[48:49] op_sel_hi:[1,0,1]
	v_pk_fma_f32 v[64:65], v[90:91], v[56:57], v[42:43] op_sel_hi:[1,0,1]
	v_lshlrev_b32_e32 v42, 16, v45
	v_and_b32_e32 v43, 0xffff0000, v45
	v_pk_fma_f32 v[50:51], v[74:75], v[56:57], v[50:51] op_sel_hi:[1,0,1]
	v_pk_fma_f32 v[52:53], v[76:77], v[56:57], v[52:53] op_sel_hi:[1,0,1]
	v_pk_mul_f32 v[58:59], v[60:61], v[58:59] op_sel_hi:[0,1]
	v_pk_mul_f32 v[42:43], v[60:61], v[42:43] op_sel_hi:[0,1]
	v_add_co_u32_e32 v74, vcc, s7, v86
	v_pk_fma_f32 v[58:59], v[78:79], v[56:57], v[58:59] op_sel_hi:[1,0,1]
	v_pk_fma_f32 v[54:55], v[54:55], v[56:57], v[42:43] op_sel_hi:[1,0,1]
	v_cvt_pk_bf16_f32 v42, v50, v51
	v_cvt_pk_bf16_f32 v43, v46, v47
	v_cvt_pk_bf16_f32 v44, v52, v53
	v_cvt_pk_bf16_f32 v45, v48, v49
	v_addc_co_u32_e32 v75, vcc, 0, v87, vcc
	global_store_dwordx4 v[74:75], v[42:45], off
	s_mov_b32 s7, 0x27c00000
	v_readlane_b32 s45, v245, 34
	v_cvt_pk_bf16_f32 v42, v58, v59
	v_cvt_pk_bf16_f32 v43, v62, v63
	v_cvt_pk_bf16_f32 v44, v64, v65
	v_cvt_pk_bf16_f32 v45, v54, v55
	global_store_dwordx4 v[74:75], v[42:45], off offset:512
	v_readlane_b32 s46, v245, 35
	v_readlane_b32 s47, v245, 36
	s_waitcnt vmcnt(60)
	v_lshlrev_b32_e32 v44, 16, v38
	v_and_b32_e32 v45, 0xffff0000, v38
	v_mov_b32_e32 v38, v61
	v_mov_b32_e32 v42, v57
	v_pk_mul_f32 v[44:45], v[38:39], v[44:45] op_sel_hi:[0,1]
	v_pk_fma_f32 v[44:45], v[50:51], v[42:43], v[44:45] op_sel_hi:[1,0,1]
	v_lshlrev_b32_e32 v50, 16, v39
	v_and_b32_e32 v51, 0xffff0000, v39
	v_pk_mul_f32 v[50:51], v[38:39], v[50:51] op_sel_hi:[0,1]
	v_pk_fma_f32 v[46:47], v[46:47], v[42:43], v[50:51] op_sel_hi:[1,0,1]
	v_lshlrev_b32_e32 v50, 16, v40
	v_and_b32_e32 v51, 0xffff0000, v40
	v_lshlrev_b32_e32 v40, 16, v41
	v_and_b32_e32 v41, 0xffff0000, v41
	v_pk_mul_f32 v[40:41], v[38:39], v[40:41] op_sel_hi:[0,1]
	v_pk_fma_f32 v[40:41], v[48:49], v[42:43], v[40:41] op_sel_hi:[1,0,1]
	s_waitcnt vmcnt(59)
	v_lshlrev_b32_e32 v48, 16, v34
	v_and_b32_e32 v49, 0xffff0000, v34
	v_lshlrev_b32_e32 v34, 16, v35
	v_and_b32_e32 v35, 0xffff0000, v35
	v_pk_mul_f32 v[50:51], v[38:39], v[50:51] op_sel_hi:[0,1]
	v_pk_mul_f32 v[34:35], v[38:39], v[34:35] op_sel_hi:[0,1]
	v_pk_fma_f32 v[50:51], v[52:53], v[42:43], v[50:51] op_sel_hi:[1,0,1]
	v_pk_fma_f32 v[52:53], v[62:63], v[42:43], v[34:35] op_sel_hi:[1,0,1]
	v_lshlrev_b32_e32 v34, 16, v36
	v_and_b32_e32 v35, 0xffff0000, v36
	v_pk_mul_f32 v[34:35], v[38:39], v[34:35] op_sel_hi:[0,1]
	v_pk_fma_f32 v[56:57], v[64:65], v[42:43], v[34:35] op_sel_hi:[1,0,1]
	v_lshlrev_b32_e32 v34, 16, v37
	v_and_b32_e32 v35, 0xffff0000, v37
	v_pk_mul_f32 v[48:49], v[38:39], v[48:49] op_sel_hi:[0,1]
	v_pk_mul_f32 v[34:35], v[38:39], v[34:35] op_sel_hi:[0,1]
	v_pk_fma_f32 v[48:49], v[58:59], v[42:43], v[48:49] op_sel_hi:[1,0,1]
	v_pk_fma_f32 v[38:39], v[54:55], v[42:43], v[34:35] op_sel_hi:[1,0,1]
	v_add_co_u32_e32 v42, vcc, s7, v86
	v_cvt_pk_bf16_f32 v34, v44, v45
	v_cvt_pk_bf16_f32 v35, v46, v47
	v_cvt_pk_bf16_f32 v36, v50, v51
	v_cvt_pk_bf16_f32 v37, v40, v41
	v_addc_co_u32_e32 v43, vcc, 0, v87, vcc
	global_store_dwordx4 v[42:43], v[34:37], off
	s_mov_b32 s7, 0x27c20000
	v_readlane_b32 s48, v245, 37
	v_cvt_pk_bf16_f32 v34, v48, v49
	v_cvt_pk_bf16_f32 v35, v52, v53
	v_cvt_pk_bf16_f32 v36, v56, v57
	v_cvt_pk_bf16_f32 v37, v38, v39
	global_store_dwordx4 v[42:43], v[34:37], off offset:512
	v_readlane_b32 s49, v245, 38
	s_waitcnt vmcnt(60)
	v_lshlrev_b32_e32 v36, 16, v32
	v_and_b32_e32 v37, 0xffff0000, v32
	v_lshlrev_b32_e32 v32, 16, v33
	v_and_b32_e32 v33, 0xffff0000, v33
	s_waitcnt lgkmcnt(0)
	v_pk_mul_f32 v[32:33], v[70:71], v[32:33] op_sel_hi:[0,1]
	v_pk_fma_f32 v[32:33], v[40:41], v[66:67], v[32:33] op_sel_hi:[1,0,1]
	s_waitcnt vmcnt(59)
	v_lshlrev_b32_e32 v40, 16, v26
	v_and_b32_e32 v41, 0xffff0000, v26
	v_lshlrev_b32_e32 v26, 16, v27
	v_and_b32_e32 v27, 0xffff0000, v27
	v_pk_mul_f32 v[26:27], v[70:71], v[26:27] op_sel_hi:[0,1]
	v_lshlrev_b32_e32 v34, 16, v30
	v_and_b32_e32 v35, 0xffff0000, v30
	v_pk_fma_f32 v[42:43], v[52:53], v[66:67], v[26:27] op_sel_hi:[1,0,1]
	v_lshlrev_b32_e32 v26, 16, v28
	v_and_b32_e32 v27, 0xffff0000, v28
	v_pk_mul_f32 v[34:35], v[70:71], v[34:35] op_sel_hi:[0,1]
	v_lshlrev_b32_e32 v30, 16, v31
	v_and_b32_e32 v31, 0xffff0000, v31
	v_pk_mul_f32 v[26:27], v[70:71], v[26:27] op_sel_hi:[0,1]
	v_pk_fma_f32 v[34:35], v[44:45], v[66:67], v[34:35] op_sel_hi:[1,0,1]
	v_pk_mul_f32 v[30:31], v[70:71], v[30:31] op_sel_hi:[0,1]
	v_pk_mul_f32 v[36:37], v[70:71], v[36:37] op_sel_hi:[0,1]
	v_pk_fma_f32 v[44:45], v[56:57], v[66:67], v[26:27] op_sel_hi:[1,0,1]
	v_lshlrev_b32_e32 v26, 16, v29
	v_and_b32_e32 v27, 0xffff0000, v29
	v_pk_fma_f32 v[30:31], v[46:47], v[66:67], v[30:31] op_sel_hi:[1,0,1]
	v_pk_fma_f32 v[36:37], v[50:51], v[66:67], v[36:37] op_sel_hi:[1,0,1]
	v_pk_mul_f32 v[40:41], v[70:71], v[40:41] op_sel_hi:[0,1]
	v_pk_mul_f32 v[26:27], v[70:71], v[26:27] op_sel_hi:[0,1]
	v_add_co_u32_e32 v46, vcc, s7, v86
	v_pk_fma_f32 v[40:41], v[48:49], v[66:67], v[40:41] op_sel_hi:[1,0,1]
	v_pk_fma_f32 v[38:39], v[38:39], v[66:67], v[26:27] op_sel_hi:[1,0,1]
	v_cvt_pk_bf16_f32 v26, v34, v35
	v_cvt_pk_bf16_f32 v27, v30, v31
	v_cvt_pk_bf16_f32 v28, v36, v37
	v_cvt_pk_bf16_f32 v29, v32, v33
	v_addc_co_u32_e32 v47, vcc, 0, v87, vcc
	global_store_dwordx4 v[46:47], v[26:29], off
	s_mov_b32 s7, 0x27c40000
	s_nop 0
	v_cvt_pk_bf16_f32 v26, v40, v41
	v_cvt_pk_bf16_f32 v27, v42, v43
	v_cvt_pk_bf16_f32 v28, v44, v45
	v_cvt_pk_bf16_f32 v29, v38, v39
	global_store_dwordx4 v[46:47], v[26:29], off offset:512
	s_waitcnt vmcnt(60)
	s_nop 0
	v_lshlrev_b32_e32 v26, 16, v22
	v_and_b32_e32 v27, 0xffff0000, v22
	v_lshlrev_b32_e32 v22, 16, v23
	v_and_b32_e32 v23, 0xffff0000, v23
	v_pk_mul_f32 v[22:23], v[70:71], v[22:23] op_sel:[1,0]
	v_lshlrev_b32_e32 v28, 16, v24
	v_pk_fma_f32 v[22:23], v[30:31], v[66:67], v[22:23] op_sel:[0,1,0]
	v_and_b32_e32 v29, 0xffff0000, v24
	v_lshlrev_b32_e32 v24, 16, v25
	v_and_b32_e32 v25, 0xffff0000, v25
	s_waitcnt vmcnt(59)
	v_lshlrev_b32_e32 v30, 16, v18
	v_and_b32_e32 v31, 0xffff0000, v18
	v_lshlrev_b32_e32 v18, 16, v19
	v_and_b32_e32 v19, 0xffff0000, v19
	v_pk_mul_f32 v[24:25], v[70:71], v[24:25] op_sel:[1,0]
	v_pk_mul_f32 v[18:19], v[70:71], v[18:19] op_sel:[1,0]
	v_pk_fma_f32 v[24:25], v[32:33], v[66:67], v[24:25] op_sel:[0,1,0]
	v_pk_fma_f32 v[32:33], v[42:43], v[66:67], v[18:19] op_sel:[0,1,0]
	v_lshlrev_b32_e32 v18, 16, v20
	v_and_b32_e32 v19, 0xffff0000, v20
	v_pk_mul_f32 v[26:27], v[70:71], v[26:27] op_sel:[1,0]
	v_pk_mul_f32 v[18:19], v[70:71], v[18:19] op_sel:[1,0]
	v_pk_fma_f32 v[26:27], v[34:35], v[66:67], v[26:27] op_sel:[0,1,0]
	v_pk_fma_f32 v[34:35], v[44:45], v[66:67], v[18:19] op_sel:[0,1,0]
	v_lshlrev_b32_e32 v18, 16, v21
	v_and_b32_e32 v19, 0xffff0000, v21
	v_pk_mul_f32 v[28:29], v[70:71], v[28:29] op_sel:[1,0]
	v_pk_mul_f32 v[18:19], v[70:71], v[18:19] op_sel:[1,0]
	v_pk_fma_f32 v[28:29], v[36:37], v[66:67], v[28:29] op_sel:[0,1,0]
	v_pk_mul_f32 v[30:31], v[70:71], v[30:31] op_sel:[1,0]
	v_pk_fma_f32 v[36:37], v[38:39], v[66:67], v[18:19] op_sel:[0,1,0]
	v_add_co_u32_e32 v38, vcc, s7, v86
	v_pk_fma_f32 v[30:31], v[40:41], v[66:67], v[30:31] op_sel:[0,1,0]
	v_cvt_pk_bf16_f32 v18, v26, v27
	v_cvt_pk_bf16_f32 v19, v22, v23
	v_cvt_pk_bf16_f32 v20, v28, v29
	v_cvt_pk_bf16_f32 v21, v24, v25
	v_addc_co_u32_e32 v39, vcc, 0, v87, vcc
	global_store_dwordx4 v[38:39], v[18:21], off
	s_mov_b32 s7, 0x27c60000
	s_nop 0
	v_cvt_pk_bf16_f32 v18, v30, v31
	v_cvt_pk_bf16_f32 v19, v32, v33
	v_cvt_pk_bf16_f32 v20, v34, v35
	v_cvt_pk_bf16_f32 v21, v36, v37
	global_store_dwordx4 v[38:39], v[18:21], off offset:512
	s_waitcnt vmcnt(60)
	s_nop 0
	v_lshlrev_b32_e32 v18, 16, v14
	v_and_b32_e32 v19, 0xffff0000, v14
	v_lshlrev_b32_e32 v14, 16, v15
	v_and_b32_e32 v15, 0xffff0000, v15
	v_pk_mul_f32 v[14:15], v[72:73], v[14:15] op_sel_hi:[0,1]
	v_pk_fma_f32 v[14:15], v[22:23], v[68:69], v[14:15] op_sel_hi:[1,0,1]
	v_lshlrev_b32_e32 v20, 16, v16
	v_and_b32_e32 v21, 0xffff0000, v16
	v_lshlrev_b32_e32 v16, 16, v17
	v_and_b32_e32 v17, 0xffff0000, v17
	s_waitcnt vmcnt(59)
	v_lshlrev_b32_e32 v22, 16, v10
	v_and_b32_e32 v23, 0xffff0000, v10
	v_lshlrev_b32_e32 v10, 16, v11
	v_and_b32_e32 v11, 0xffff0000, v11
	v_pk_mul_f32 v[16:17], v[72:73], v[16:17] op_sel_hi:[0,1]
	v_pk_mul_f32 v[10:11], v[72:73], v[10:11] op_sel_hi:[0,1]
	v_pk_fma_f32 v[16:17], v[24:25], v[68:69], v[16:17] op_sel_hi:[1,0,1]
	v_pk_fma_f32 v[24:25], v[32:33], v[68:69], v[10:11] op_sel_hi:[1,0,1]
	v_lshlrev_b32_e32 v10, 16, v12
	v_and_b32_e32 v11, 0xffff0000, v12
	v_pk_mul_f32 v[18:19], v[72:73], v[18:19] op_sel_hi:[0,1]
	v_pk_mul_f32 v[10:11], v[72:73], v[10:11] op_sel_hi:[0,1]
	v_pk_fma_f32 v[18:19], v[26:27], v[68:69], v[18:19] op_sel_hi:[1,0,1]
	v_pk_mul_f32 v[20:21], v[72:73], v[20:21] op_sel_hi:[0,1]
	v_pk_mul_f32 v[22:23], v[72:73], v[22:23] op_sel_hi:[0,1]
	v_pk_fma_f32 v[26:27], v[34:35], v[68:69], v[10:11] op_sel_hi:[1,0,1]
	v_lshlrev_b32_e32 v10, 16, v13
	v_and_b32_e32 v11, 0xffff0000, v13
	v_pk_fma_f32 v[20:21], v[28:29], v[68:69], v[20:21] op_sel_hi:[1,0,1]
	v_pk_fma_f32 v[22:23], v[30:31], v[68:69], v[22:23] op_sel_hi:[1,0,1]
	v_pk_mul_f32 v[10:11], v[72:73], v[10:11] op_sel_hi:[0,1]
	v_add_co_u32_e32 v30, vcc, s7, v86
	v_pk_fma_f32 v[28:29], v[36:37], v[68:69], v[10:11] op_sel_hi:[1,0,1]
	v_cvt_pk_bf16_f32 v10, v18, v19
	v_cvt_pk_bf16_f32 v11, v14, v15
	v_cvt_pk_bf16_f32 v12, v20, v21
	v_cvt_pk_bf16_f32 v13, v16, v17
	v_addc_co_u32_e32 v31, vcc, 0, v87, vcc
	global_store_dwordx4 v[30:31], v[10:13], off
	s_mov_b32 s7, 0x27c80000
	s_nop 0
	v_cvt_pk_bf16_f32 v10, v22, v23
	v_cvt_pk_bf16_f32 v11, v24, v25
	v_cvt_pk_bf16_f32 v12, v26, v27
	v_cvt_pk_bf16_f32 v13, v28, v29
	global_store_dwordx4 v[30:31], v[10:13], off offset:512
	s_waitcnt vmcnt(60)
	s_nop 0
	v_lshlrev_b32_e32 v12, 16, v6
	v_and_b32_e32 v13, 0xffff0000, v6
	v_mov_b32_e32 v6, v73
	v_mov_b32_e32 v10, v69
	v_pk_mul_f32 v[12:13], v[6:7], v[12:13] op_sel_hi:[0,1]
	v_pk_fma_f32 v[90:91], v[18:19], v[10:11], v[12:13] op_sel_hi:[1,0,1]
	v_lshlrev_b32_e32 v12, 16, v7
	v_and_b32_e32 v13, 0xffff0000, v7
	v_pk_mul_f32 v[12:13], v[6:7], v[12:13] op_sel_hi:[0,1]
	v_pk_fma_f32 v[92:93], v[14:15], v[10:11], v[12:13] op_sel_hi:[1,0,1]
	v_lshlrev_b32_e32 v12, 16, v8
	v_and_b32_e32 v13, 0xffff0000, v8
	v_lshlrev_b32_e32 v8, 16, v9
	v_and_b32_e32 v9, 0xffff0000, v9
	v_pk_mul_f32 v[8:9], v[6:7], v[8:9] op_sel_hi:[0,1]
	v_pk_fma_f32 v[96:97], v[16:17], v[10:11], v[8:9] op_sel_hi:[1,0,1]
	s_waitcnt vmcnt(59)
	v_lshlrev_b32_e32 v8, 16, v2
	v_and_b32_e32 v9, 0xffff0000, v2
	v_lshlrev_b32_e32 v2, 16, v3
	v_and_b32_e32 v3, 0xffff0000, v3
	v_pk_mul_f32 v[2:3], v[6:7], v[2:3] op_sel_hi:[0,1]
	v_pk_fma_f32 v[100:101], v[24:25], v[10:11], v[2:3] op_sel_hi:[1,0,1]
	v_lshlrev_b32_e32 v2, 16, v4
	v_and_b32_e32 v3, 0xffff0000, v4
	v_pk_mul_f32 v[2:3], v[6:7], v[2:3] op_sel_hi:[0,1]
	v_pk_mul_f32 v[12:13], v[6:7], v[12:13] op_sel_hi:[0,1]
	v_pk_fma_f32 v[102:103], v[26:27], v[10:11], v[2:3] op_sel_hi:[1,0,1]
	v_lshlrev_b32_e32 v2, 16, v5
	v_and_b32_e32 v3, 0xffff0000, v5
	v_pk_fma_f32 v[94:95], v[20:21], v[10:11], v[12:13] op_sel_hi:[1,0,1]
	v_pk_mul_f32 v[8:9], v[6:7], v[8:9] op_sel_hi:[0,1]
	v_pk_mul_f32 v[2:3], v[6:7], v[2:3] op_sel_hi:[0,1]
	v_add_co_u32_e32 v6, vcc, s7, v86
	v_pk_fma_f32 v[98:99], v[22:23], v[10:11], v[8:9] op_sel_hi:[1,0,1]
	v_pk_fma_f32 v[104:105], v[28:29], v[10:11], v[2:3] op_sel_hi:[1,0,1]
	v_cvt_pk_bf16_f32 v2, v90, v91
	v_cvt_pk_bf16_f32 v3, v92, v93
	v_cvt_pk_bf16_f32 v4, v94, v95
	v_cvt_pk_bf16_f32 v5, v96, v97
	v_addc_co_u32_e32 v7, vcc, 0, v87, vcc
	global_store_dwordx4 v[6:7], v[2:5], off
	s_mov_b32 s7, 0x23c80000
	s_nop 0
	v_cvt_pk_bf16_f32 v2, v98, v99
	v_cvt_pk_bf16_f32 v3, v100, v101
	v_cvt_pk_bf16_f32 v4, v102, v103
	v_cvt_pk_bf16_f32 v5, v104, v105
	global_store_dwordx4 v[6:7], v[2:5], off offset:512
	s_nop 1
	v_add_co_u32_e32 v2, vcc, s7, v88
	s_mov_b32 s7, 0
	s_nop 0
	v_addc_co_u32_e32 v3, vcc, 0, v89, vcc
	s_waitcnt vmcnt(45)
	v_mov_b32_e32 v78, v110
	v_mov_b32_e32 v79, v111
	v_mov_b32_e32 v80, v112
	v_mov_b32_e32 v81, v113
	v_lshl_add_u64 v[2:3], v[88:89], 0, s[8:9]
	v_mov_b32_e32 v74, v114
	v_mov_b32_e32 v75, v115
	v_mov_b32_e32 v76, v116
	v_mov_b32_e32 v77, v117
	s_mov_b64 s[8:9], 0x23ca0000
	v_lshl_add_u64 v[2:3], v[88:89], 0, s[8:9]
	s_mov_b32 s8, 0x23ca0000
	v_add_co_u32_e32 v4, vcc, s8, v88
	s_mov_b64 s[8:9], 0x23cc0000
	s_nop 0
	v_addc_co_u32_e32 v5, vcc, 0, v89, vcc
	v_mov_b32_e32 v70, v118
	v_mov_b32_e32 v71, v119
	v_mov_b32_e32 v72, v120
	v_mov_b32_e32 v73, v121
	v_mov_b32_e32 v58, v122
	v_mov_b32_e32 v59, v123
	v_mov_b32_e32 v60, v124
	v_mov_b32_e32 v61, v125
	v_lshl_add_u64 v[2:3], v[88:89], 0, s[8:9]
	s_mov_b32 s8, 0x23cc0000
	v_add_co_u32_e32 v4, vcc, s8, v88
	s_mov_b64 s[8:9], 0x23ce0000
	s_nop 0
	v_addc_co_u32_e32 v5, vcc, 0, v89, vcc
	v_mov_b32_e32 v54, v126
	v_mov_b32_e32 v55, v127
	v_mov_b32_e32 v56, v128
	v_mov_b32_e32 v57, v129
	v_mov_b32_e32 v42, v130
	v_mov_b32_e32 v43, v131
	v_mov_b32_e32 v44, v132
	v_mov_b32_e32 v45, v133
	v_lshl_add_u64 v[2:3], v[88:89], 0, s[8:9]
	s_mov_b32 s8, 0x23ce0000
	v_add_co_u32_e32 v4, vcc, s8, v88
	s_mov_b64 s[8:9], 0x23d00000
	s_nop 0
	v_addc_co_u32_e32 v5, vcc, 0, v89, vcc
	v_mov_b32_e32 v38, v134
	v_mov_b32_e32 v39, v135
	v_mov_b32_e32 v40, v136
	v_mov_b32_e32 v41, v137
	v_mov_b32_e32 v34, v138
	v_mov_b32_e32 v35, v139
	v_mov_b32_e32 v36, v140
	v_mov_b32_e32 v37, v141
	v_lshl_add_u64 v[2:3], v[88:89], 0, s[8:9]
	s_mov_b32 s8, 0x23d00000
	v_add_co_u32_e32 v4, vcc, s8, v88
	s_mov_b64 s[8:9], 0x23d20000
	s_nop 0
	v_addc_co_u32_e32 v5, vcc, 0, v89, vcc
	v_mov_b32_e32 v30, v142
	v_mov_b32_e32 v31, v143
	v_mov_b32_e32 v32, v144
	v_mov_b32_e32 v33, v145
	v_mov_b32_e32 v26, v146
	v_mov_b32_e32 v27, v147
	v_mov_b32_e32 v28, v148
	v_mov_b32_e32 v29, v149
	v_lshl_add_u64 v[2:3], v[88:89], 0, s[8:9]
	s_mov_b32 s8, 0x23d20000
	v_add_co_u32_e32 v4, vcc, s8, v88
	s_mov_b64 s[8:9], 0x23d40000
	s_nop 0
	v_addc_co_u32_e32 v5, vcc, 0, v89, vcc
	v_mov_b32_e32 v22, v150
	v_mov_b32_e32 v23, v151
	v_mov_b32_e32 v24, v152
	v_mov_b32_e32 v25, v153
	v_mov_b32_e32 v18, v154
	v_mov_b32_e32 v19, v155
	v_mov_b32_e32 v20, v156
	v_mov_b32_e32 v21, v157
	v_lshl_add_u64 v[2:3], v[88:89], 0, s[8:9]
	s_mov_b32 s8, 0x23d40000
	v_add_co_u32_e32 v4, vcc, s8, v88
	s_mov_b64 s[8:9], 0x23d60000
	s_nop 0
	v_addc_co_u32_e32 v5, vcc, 0, v89, vcc
	v_mov_b32_e32 v14, v158
	v_mov_b32_e32 v15, v159
	v_mov_b32_e32 v16, v160
	v_mov_b32_e32 v17, v161
	v_mov_b32_e32 v10, v162
	v_mov_b32_e32 v11, v163
	v_mov_b32_e32 v12, v164
	v_mov_b32_e32 v13, v165
	v_lshl_add_u64 v[46:47], v[88:89], 0, s[8:9]
	s_mov_b32 s8, 0x23d60000
	v_add_co_u32_e32 v48, vcc, s8, v88
	s_mov_b32 s8, 0x27ca0000
	s_nop 0
	v_addc_co_u32_e32 v49, vcc, 0, v89, vcc
	v_mov_b32_e32 v6, v166
	v_mov_b32_e32 v7, v167
	v_mov_b32_e32 v8, v168
	v_mov_b32_e32 v9, v169
	v_mov_b32_e32 v2, v170
	v_mov_b32_e32 v3, v171
	v_mov_b32_e32 v4, v172
	v_mov_b32_e32 v5, v173
	v_cmp_gt_i32_e32 vcc, 0x100, v84
	s_and_b64 s[12:13], s[2:3], vcc
	s_and_saveexec_b64 s[14:15], s[12:13]
	s_cbranch_execz .Lmy_p3_nonrm
	s_lshl_b64 s[12:13], s[4:5], 2
	s_add_u32 s12, s12, s96
	s_addc_u32 s13, s13, s97
	v_mov_b32_e32 v130, v84
	v_ashrrev_i32_e32 v131, 31, v84
	v_lshlrev_b64 v[130:131], 2, v[130:131]
	v_lshl_add_u64 v[130:131], s[12:13], 0, v[130:131]
	s_mov_b64 s[12:13], 0x2bb80000
	v_lshl_add_u64 v[132:133], v[130:131], 0, s[12:13]
	global_load_dword v114, v[132:133], off
	global_load_dword v115, v[132:133], off offset:1024
	global_load_dword v116, v[132:133], off offset:2048
	global_load_dword v117, v[132:133], off offset:3072
	s_mov_b64 s[12:13], 0x2bb81000
	v_lshl_add_u64 v[132:133], v[130:131], 0, s[12:13]
	global_load_dword v118, v[132:133], off
	global_load_dword v119, v[132:133], off offset:1024
	global_load_dword v120, v[132:133], off offset:2048
	global_load_dword v121, v[132:133], off offset:3072
	s_mov_b64 s[12:13], 0x2bb82000
	v_lshl_add_u64 v[132:133], v[130:131], 0, s[12:13]
	global_load_dword v122, v[132:133], off
	global_load_dword v123, v[132:133], off offset:1024
	global_load_dword v124, v[132:133], off offset:2048
	global_load_dword v125, v[132:133], off offset:3072
	s_mov_b64 s[12:13], 0x2bb83000
	v_lshl_add_u64 v[132:133], v[130:131], 0, s[12:13]
	global_load_dword v126, v[132:133], off
	global_load_dword v127, v[132:133], off offset:1024
	global_load_dword v128, v[132:133], off offset:2048
	global_load_dword v129, v[132:133], off offset:3072

.LBB0_958:
	s_or_b64 exec, exec, s[2:3]
	v_mov_b32_e32 v1, v0
	s_barrier
	v_readlane_b32 s0, v245, 9
	v_and_b32_e32 v13, 63, v1
	v_lshlrev_b32_e32 v6, 2, v13
	v_readlane_b32 s12, v245, 21
	v_readlane_b32 s13, v245, 22
	v_readlane_b32 s14, v245, 23
	v_readlane_b32 s15, v245, 24
	s_nop 2
	s_waitcnt vmcnt(34)
	v_mov_b32_e32 v4, v106
	s_nop 0
	v_mov_b32_e32 v5, v107
	v_mov_b32_e32 v7, v108
	v_mov_b32_e32 v8, v109
	v_lshlrev_b32_e32 v2, 3, v13
	v_mov_b32_e32 v2, v174
	v_mov_b32_e32 v3, v175
	v_readlane_b32 s2, v245, 11
	s_mov_b32 s2, 0x3fb8aa3b
	v_readlane_b32 s3, v245, 12
	s_mov_b32 s3, 0xc2ce8ed0
	v_readlane_b32 s6, v245, 15
	v_readlane_b32 s1, v245, 10
	s_mov_b32 s6, 0x42b17218
	v_readfirstlane_b32 s20, v1
	s_lshl_b32 s1, s92, 3
	v_mov_b32_e32 v9, 0x7f800000
	s_ashr_i32 s0, s20, 6
	v_readlane_b32 s4, v245, 13
	s_add_i32 s33, s0, s1
	v_readlane_b32 s5, v245, 14
	s_add_u32 s4, s96, 0x10f00000
	v_lshlrev_b32_e32 v14, 1, v13
	s_addc_u32 s5, s97, 0
	s_cmpk_gt_i32 s33, 0x1fff
	v_readlane_b32 s7, v245, 16
	v_readlane_b32 s8, v245, 17
	v_readlane_b32 s9, v245, 18
	v_readlane_b32 s10, v245, 19
	v_readlane_b32 s11, v245, 20
	v_mul_f32_e32 v10, v4, v5
	s_nop 1
	v_mov_b32_dpp v10, v10 quad_perm:[1,0,3,2] row_mask:0xf bank_mask:0xf bound_ctrl:1
	v_mul_f32_e32 v11, v7, v8
	v_fmac_f32_e32 v10, v4, v5
	s_nop 0
	v_mov_b32_dpp v11, v11 quad_perm:[1,0,3,2] row_mask:0xf bank_mask:0xf bound_ctrl:1
	v_fmac_f32_e32 v11, v7, v8
	v_add_f32_dpp v4, v10, v10 quad_perm:[2,3,0,1] row_mask:0xf bank_mask:0xf bound_ctrl:1
	s_nop 0
	v_add_f32_dpp v5, v11, v11 quad_perm:[2,3,0,1] row_mask:0xf bank_mask:0xf bound_ctrl:1
	v_add_f32_dpp v4, v4, v4 row_ror:4 row_mask:0xf bank_mask:0xf bound_ctrl:1
	s_nop 0
	v_add_f32_dpp v5, v5, v5 row_ror:4 row_mask:0xf bank_mask:0xf bound_ctrl:1
	v_add_f32_dpp v4, v4, v4 row_ror:8 row_mask:0xf bank_mask:0xf bound_ctrl:1
	v_mov_b32_e32 v7, v4
	v_add_f32_dpp v5, v5, v5 row_ror:8 row_mask:0xf bank_mask:0xf bound_ctrl:1
	v_mov_b32_e32 v8, v5
	v_permlane16_swap_b32_e32 v4, v7
	s_nop 0
	v_permlane16_swap_b32_e32 v5, v8
	v_add_f32_e32 v4, v4, v7
	v_add_f32_e32 v5, v5, v8
	v_mov_b32_e32 v7, v4
	v_mov_b32_e32 v8, v5
	s_nop 0
	v_permlane32_swap_b32_e32 v4, v7
	v_permlane32_swap_b32_e32 v5, v8
	v_add_f32_e32 v4, v4, v7
	v_add_f32_e32 v5, v5, v8
	v_mul_f32_e32 v7, 0x3fb8aa3b, v4
	v_mul_f32_e32 v8, 0x3fb8aa3b, v5
	v_fma_f32 v10, v4, s2, -v7
	v_rndne_f32_e32 v11, v7
	v_fma_f32 v12, v5, s2, -v8
	v_rndne_f32_e32 v15, v8
	v_fmac_f32_e32 v10, 0x32a5705f, v4
	v_sub_f32_e32 v7, v7, v11
	v_fmac_f32_e32 v12, 0x32a5705f, v5
	v_sub_f32_e32 v8, v8, v15
	v_add_f32_e32 v7, v7, v10
	v_cvt_i32_f32_e32 v11, v11
	v_add_f32_e32 v8, v8, v12
	v_exp_f32_e32 v7, v7
	v_cvt_i32_f32_e32 v15, v15
	v_exp_f32_e32 v8, v8
	v_cmp_ngt_f32_e32 vcc, s3, v4
	v_ldexp_f32 v7, v7, v11
	v_ldexp_f32 v8, v8, v15
	v_cndmask_b32_e32 v7, 0, v7, vcc
	v_cmp_ngt_f32_e32 vcc, s3, v5
	s_nop 1
	v_cndmask_b32_e32 v8, 0, v8, vcc
	v_cmp_nlt_f32_e32 vcc, s6, v4
	s_nop 1
	v_cndmask_b32_e32 v4, v9, v7, vcc
	v_cmp_nlt_f32_e32 vcc, s6, v5
	s_nop 1
	v_cndmask_b32_e32 v5, v9, v8, vcc
	v_sub_f32_e32 v4, v4, v5
	v_add_f32_e32 v4, 0x3e4ccccd, v4
	v_lshlrev_b32_e32 v8, 1, v14
	s_cbranch_scc1 .LBB0_963
	s_add_u32 s1, s96, 0x19000000
	s_addc_u32 s14, s97, 0
	s_lshl_b32 s2, s33, 1
	s_ashr_i32 s3, s2, 31
	s_lshl_b64 s[6:7], s[2:3], 11
	s_add_u32 s6, s1, s6
	s_addc_u32 s7, s14, s7
	s_lshl_b64 s[8:9], s[2:3], 12
	s_add_u32 s10, s4, s8
	s_addc_u32 s11, s5, s9
	v_mov_b32_e32 v11, v176
	v_mov_b32_e32 v10, v177
	v_mov_b32_e32 v59, v178
	v_mov_b32_e32 v58, v179
	v_mov_b32_e32 v56, v180
	v_mov_b32_e32 v55, v181
	v_mov_b32_e32 v53, v182
	v_mov_b32_e32 v52, v183
	s_or_b32 s6, s2, 1
	s_mov_b32 s7, s3
	s_lshl_b64 s[12:13], s[6:7], 11
	s_add_u32 s12, s1, s12
	s_addc_u32 s13, s14, s13
	s_lshl_b64 s[6:7], s[6:7], 12
	s_add_u32 s6, s4, s6
	v_mov_b32_e32 v60, v184
	v_mov_b32_e32 v57, v185
	v_mov_b32_e32 v54, v186
	v_mov_b32_e32 v50, v187
	v_mov_b32_e32 v51, v188
	v_mov_b32_e32 v49, v189
	v_mov_b32_e32 v47, v190
	v_mov_b32_e32 v46, v191
	v_mov_b32_e32 v43, v193
	s_addc_u32 s7, s5, s7
	v_mov_b32_e32 v44, v192
	v_mov_b32_e32 v48, v196
	v_mov_b32_e32 v45, v197
	v_mov_b32_e32 v25, v198
	v_mov_b32_e32 v15, v199
	v_mov_b32_e32 v22, v195
	v_mov_b32_e32 v26, v194
	s_lshl_b32 s6, s95, 4
	s_add_u32 s8, s96, s8
	s_addc_u32 s9, s97, s9
	s_lshl_b32 s1, s92, 4
	s_lshl_b32 s0, s0, 1
	s_add_i32 s1, s1, s6
	s_add_i32 s0, s1, s0
	s_ashr_i32 s7, s6, 31
	s_ashr_i32 s1, s0, 31
	s_lshl_b64 s[10:11], s[6:7], 12
	s_lshl_b64 s[12:13], s[0:1], 12
	s_add_u32 s12, s96, s12
	s_addc_u32 s13, s97, s13
	s_lshl_b64 s[0:1], s[0:1], 11
	s_add_u32 s14, s96, s0
	v_mov_b32_e32 v5, v4
	v_mov_b32_e32 v7, 0
	v_mov_b32_e32 v9, 0x3727c5ac
	s_mov_b32 s3, 0xf800000
	v_mov_b32_e32 v12, 0x260
	s_mov_b32 s21, 0x3f4ccccd
	s_mov_b32 s22, 0x1b000000
	s_mov_b32 s23, 0x1b001000
	s_addc_u32 s15, s97, s1
	s_lshl_b64 s[16:17], s[6:7], 11
	v_mov_b32_e32 v18, v11
	v_mov_b32_e32 v16, v10
	v_mov_b32_e32 v20, v59
	v_mov_b32_e32 v17, v58
	v_mov_b32_e32 v23, v56
	v_mov_b32_e32 v19, v55
	v_mov_b32_e32 v24, v53
	v_mov_b32_e32 v21, v52
	v_mov_b32_e32 v30, v60
	v_mov_b32_e32 v32, v57
	v_mov_b32_e32 v34, v54
	v_mov_b32_e32 v36, v50
	v_mov_b32_e32 v27, v49
	v_mov_b32_e32 v28, v51
	v_mov_b32_e32 v29, v46
	v_mov_b32_e32 v33, v43
	v_mov_b32_e32 v31, v47
	v_mov_b32_e32 v35, v44
	v_mov_b32_e32 v39, v48
	v_mov_b32_e32 v40, v45
	v_mov_b32_e32 v41, v25
	v_mov_b32_e32 v42, v15
	v_mov_b32_e32 v37, v22
	v_mov_b32_e32 v38, v26
	s_branch .LBB0_961
